# v009 plus: in-proj and MLP-up clear each accumulator right behind its last use in the (store-bound) tile epilogue instead of in front of the next K loop
# baseline (speedup 1.0000x reference)
.LBB0_177:
	v_readlane_b32 s18, v254, 38
	v_readlane_b32 s19, v254, 39
	s_lshl_b64 s[18:19], s[18:19], 2
	s_add_u32 s18, s12, s18
	s_addc_u32 s19, s13, s19
	s_cmp_eq_u64 s[12:13], 0
	s_cselect_b64 s[40:41], -1, 0
	s_cmp_lg_u64 s[12:13], 0
	s_cselect_b64 s[42:43], -1, 0
	s_add_u32 s63, s38, 0x18000000
	s_addc_u32 s64, s39, 0
	s_lshl_b32 s12, s28, 5
	s_and_b32 s28, s12, 0x60
	s_add_i32 m0, s59, 0x18000
	v_lshl_add_u64 v[8:9], v[8:9], 0, s[10:11]
	s_lshl_b32 s29, s21, 13
	s_lshl_b32 s33, s28, 7
	s_waitcnt vmcnt(2)
	s_barrier
	global_load_lds_dwordx4 v[8:9], off
	v_lshl_add_u64 v[6:7], v[6:7], 0, s[10:11]
	s_add_i32 m0, s59, 0x1a000
	s_add_i32 s65, s59, 0x8000
	s_add_i32 s66, s59, 0xa000
	global_load_lds_dwordx4 v[6:7], off
	v_lshl_add_u64 v[2:3], v[2:3], 0, s[10:11]
	s_mov_b32 m0, s65
	s_add_u32 s12, s4, 0x40080
	global_load_lds_dwordx4 v[2:3], off
	v_lshl_add_u64 v[2:3], v[4:5], 0, s[10:11]
	s_mov_b32 m0, s66
	s_addc_u32 s13, s5, 0
	global_load_lds_dwordx4 v[2:3], off
	s_add_i32 m0, s59, 0x1c000
	v_lshl_add_u64 v[2:3], s[12:13], 0, v[134:135]
	global_load_lds_dwordx4 v[2:3], off
	v_lshl_add_u64 v[2:3], s[12:13], 0, v[130:131]
	s_add_i32 m0, s59, 0x1e000
	v_readlane_b32 s12, v255, 60
	global_load_lds_dwordx4 v[2:3], off
	v_lshrrev_b32_e32 v3, 1, v0
	v_and_b32_e32 v3, 24, v3
	v_and_b32_e32 v2, 15, v0
	v_lshlrev_b32_e32 v4, 1, v3
	v_lshlrev_b32_e32 v0, 2, v0
	v_lshl_or_b32 v143, s21, 6, v2
	v_lshl_or_b32 v2, v2, 6, v4
	v_and_b32_e32 v0, 32, v0
	v_bitop3_b32 v4, v2, s29, v0 bitop3:0xde
	v_bitop3_b32 v147, v2, s33, v0 bitop3:0xde
	v_lshlrev_b32_e32 v2, 14, v10
	v_and_b32_e32 v2, 0xffff8000, v2
	v_or_b32_e32 v0, s28, v3
	v_lshl_add_u32 v2, v11, 11, v2
	v_and_b32_e32 v3, 1, v10
	v_lshl_or_b32 v2, v3, 6, v2
	v_lshl_add_u32 v138, v12, 1, v2
	v_lshlrev_b32_e32 v2, 14, v14
	v_and_b32_e32 v2, 0xffff8000, v2
	s_waitcnt vmcnt(6)
	v_lshl_add_u32 v2, v13, 11, v2
	v_and_b32_e32 v3, 1, v14
	s_cmpk_lt_u32 s20, 0x100
	v_lshl_or_b32 v2, v3, 6, v2
	s_mov_b32 s52, s12
	v_readlane_b32 s12, v254, 3
	s_cselect_b64 s[44:45], -1, 0
	v_mov_b32_e32 v139, v1
	v_lshl_add_u32 v140, v15, 1, v2
	v_mov_b32_e32 v141, v1
	s_mov_b32 s36, 0
	v_add_u32_e32 v149, 0, v4
	v_lshlrev_b32_e32 v0, 1, v0
	s_mov_b32 s20, s12
	s_barrier
	v_readlane_b32 s13, v254, 4
	v_lshl_add_u32 v238, s20, 8, v143
	v_mov_b32_e32 v239, 0
	v_lshl_add_u64 v[238:239], v[238:239], 2, s[18:19]
	global_load_dword v240, v[238:239], off
	global_load_dword v241, v[238:239], off offset:64
	global_load_dword v242, v[238:239], off offset:128
	global_load_dword v243, v[238:239], off offset:192
	global_load_dword v244, v[238:239], off offset:512
	global_load_dword v245, v[238:239], off offset:576
	global_load_dword v246, v[238:239], off offset:640
	global_load_dword v247, v[238:239], off offset:704
	v_mov_b32_e32 v6, 0
	v_mov_b32_e32 v7, 0
	v_mov_b32_e32 v8, 0
	v_mov_b32_e32 v9, 0
	v_mov_b32_e32 v10, 0
	v_mov_b32_e32 v11, 0
	v_mov_b32_e32 v12, 0
	v_mov_b32_e32 v13, 0
	v_mov_b32_e32 v16, 0
	v_mov_b32_e32 v17, 0
	v_mov_b32_e32 v18, 0
	v_mov_b32_e32 v19, 0
	v_mov_b32_e32 v20, 0
	v_mov_b32_e32 v21, 0
	v_mov_b32_e32 v22, 0
	v_mov_b32_e32 v23, 0
	v_mov_b32_e32 v24, 0
	v_mov_b32_e32 v25, 0
	v_mov_b32_e32 v26, 0
	v_mov_b32_e32 v27, 0
	v_mov_b32_e32 v28, 0
	v_mov_b32_e32 v29, 0
	v_mov_b32_e32 v30, 0
	v_mov_b32_e32 v31, 0
	v_mov_b32_e32 v32, 0
	v_mov_b32_e32 v33, 0
	v_mov_b32_e32 v34, 0
	v_mov_b32_e32 v35, 0
	v_mov_b32_e32 v36, 0
	v_mov_b32_e32 v37, 0
	v_mov_b32_e32 v38, 0
	v_mov_b32_e32 v39, 0
	v_mov_b32_e32 v40, 0
	v_mov_b32_e32 v41, 0
	v_mov_b32_e32 v42, 0
	v_mov_b32_e32 v43, 0
	v_mov_b32_e32 v44, 0
	v_mov_b32_e32 v45, 0
	v_mov_b32_e32 v46, 0
	v_mov_b32_e32 v47, 0
	v_mov_b32_e32 v48, 0
	v_mov_b32_e32 v49, 0
	v_mov_b32_e32 v50, 0
	v_mov_b32_e32 v51, 0
	v_mov_b32_e32 v52, 0
	v_mov_b32_e32 v53, 0
	v_mov_b32_e32 v54, 0
	v_mov_b32_e32 v55, 0
	v_mov_b32_e32 v56, 0
	v_mov_b32_e32 v57, 0
	v_mov_b32_e32 v58, 0
	v_mov_b32_e32 v59, 0
	v_mov_b32_e32 v60, 0
	v_mov_b32_e32 v61, 0
	v_mov_b32_e32 v62, 0
	v_mov_b32_e32 v63, 0
	v_mov_b32_e32 v64, 0
	v_mov_b32_e32 v65, 0
	v_mov_b32_e32 v66, 0
	v_mov_b32_e32 v67, 0
	v_mov_b32_e32 v68, 0
	v_mov_b32_e32 v69, 0
	v_mov_b32_e32 v70, 0
	v_mov_b32_e32 v71, 0
	v_mov_b32_e32 v72, 0
	v_mov_b32_e32 v73, 0
	v_mov_b32_e32 v74, 0
	v_mov_b32_e32 v75, 0
	v_mov_b32_e32 v76, 0
	v_mov_b32_e32 v77, 0
	v_mov_b32_e32 v78, 0
	v_mov_b32_e32 v79, 0
	v_mov_b32_e32 v80, 0
	v_mov_b32_e32 v81, 0
	v_mov_b32_e32 v82, 0
	v_mov_b32_e32 v83, 0
	v_mov_b32_e32 v84, 0
	v_mov_b32_e32 v85, 0
	v_mov_b32_e32 v86, 0
	v_mov_b32_e32 v87, 0
	v_mov_b32_e32 v88, 0
	v_mov_b32_e32 v89, 0
	v_mov_b32_e32 v90, 0
	v_mov_b32_e32 v91, 0
	v_mov_b32_e32 v92, 0
	v_mov_b32_e32 v93, 0
	v_mov_b32_e32 v94, 0
	v_mov_b32_e32 v95, 0
	v_mov_b32_e32 v96, 0
	v_mov_b32_e32 v97, 0
	v_mov_b32_e32 v98, 0
	v_mov_b32_e32 v99, 0
	v_mov_b32_e32 v100, 0
	v_mov_b32_e32 v101, 0
	v_mov_b32_e32 v102, 0
	v_mov_b32_e32 v103, 0
	v_mov_b32_e32 v104, 0
	v_mov_b32_e32 v105, 0
	v_mov_b32_e32 v106, 0
	v_mov_b32_e32 v107, 0
	v_mov_b32_e32 v108, 0
	v_mov_b32_e32 v109, 0
	v_mov_b32_e32 v110, 0
	v_mov_b32_e32 v111, 0
	v_mov_b32_e32 v112, 0
	v_mov_b32_e32 v113, 0
	v_mov_b32_e32 v114, 0
	v_mov_b32_e32 v115, 0
	v_mov_b32_e32 v116, 0
	v_mov_b32_e32 v117, 0
	v_mov_b32_e32 v118, 0
	v_mov_b32_e32 v119, 0
	v_mov_b32_e32 v120, 0
	v_mov_b32_e32 v121, 0
	v_mov_b32_e32 v122, 0
	v_mov_b32_e32 v123, 0
	v_mov_b32_e32 v124, 0
	v_mov_b32_e32 v125, 0
	v_mov_b32_e32 v126, 0
	v_mov_b32_e32 v127, 0
	v_mov_b32_e32 v128, 0
	v_mov_b32_e32 v129, 0
	s_branch .LBB0_180

.LBB0_182:
	s_ashr_i32 s49, s48, 31
	s_lshl_b64 s[12:13], s[48:49], 19
	s_add_u32 s12, s0, s12
	s_addc_u32 s13, s17, s13
	s_and_b64 s[28:29], s[38:39], exec
	s_cselect_b32 s21, s13, s15
	s_cselect_b32 s28, s12, s14
	s_ashr_i32 s47, s46, 31
	s_lshl_b64 s[50:51], s[46:47], 19
	s_add_u32 s50, s56, s50
	s_addc_u32 s51, s57, s51
	s_and_b64 s[54:55], s[38:39], exec
	s_cselect_b32 s29, s51, s5
	s_cselect_b32 s33, s50, s4
	s_add_u32 s37, s4, 0x100
	s_addc_u32 s47, s5, 0
	s_add_u32 s4, s14, 0x40080
	v_mov_b32_e32 v2, 0
	s_addc_u32 s5, s15, 0
	s_mov_b32 s49, -2
	v_mov_b32_e32 v3, v2
	v_mov_b32_e32 v4, v2
	v_mov_b32_e32 v5, v2
	v_mov_b32_e32 v14, v2
	v_mov_b32_e32 v15, v2

.LBB0_186:
	v_lshl_add_u32 v144, s20, 8, v143
	v_ashrrev_i32_e32 v145, 31, v144
	s_waitcnt vmcnt(8)
	v_fmamk_f32 v146, v240, 0x3a800000, v225
	v_fmamk_f32 v142, v241, 0x3a800000, v225
	v_fmamk_f32 v150, v242, 0x3a800000, v225
	v_fmamk_f32 v148, v243, 0x3a800000, v225
	v_fmamk_f32 v152, v244, 0x3a800000, v225
	v_fmamk_f32 v151, v245, 0x3a800000, v225
	v_fmamk_f32 v153, v246, 0x3a800000, v225
	v_fmamk_f32 v154, v247, 0x3a800000, v225
	s_and_b64 s[4:5], s[38:39], exec
	s_cselect_b32 s4, s48, s20
	v_lshl_add_u32 v238, s4, 8, v143
	v_mov_b32_e32 v239, 0
	v_lshl_add_u64 v[238:239], v[238:239], 2, s[18:19]
	global_load_dword v240, v[238:239], off
	global_load_dword v241, v[238:239], off offset:64
	global_load_dword v242, v[238:239], off offset:128
	global_load_dword v243, v[238:239], off offset:192
	global_load_dword v244, v[238:239], off offset:512
	global_load_dword v245, v[238:239], off offset:576
	global_load_dword v246, v[238:239], off offset:640
	global_load_dword v247, v[238:239], off offset:704
	v_rsq_f32_e32 v142, v142
	v_rsq_f32_e32 v146, v146
	v_rsq_f32_e32 v150, v150
	s_ashr_i32 s53, s52, 31
	v_cndmask_b32_e64 v158, v142, 1.0, s[40:41]
	v_rsq_f32_e32 v142, v152
	v_rsq_f32_e32 v152, v154
	s_lshl_b64 s[4:5], s[52:53], 25
	s_add_u32 s4, s63, s4
	v_cndmask_b32_e64 v156, v146, 1.0, s[40:41]
	v_cndmask_b32_e64 v160, v150, 1.0, s[40:41]
	v_rsq_f32_e32 v146, v151
	v_rsq_f32_e32 v151, v153
	v_cndmask_b32_e64 v150, v142, 1.0, s[40:41]
	v_cndmask_b32_e64 v142, v152, 1.0, s[40:41]
	s_addc_u32 s5, s64, s5
	v_lshlrev_b64 v[152:153], 9, v[144:145]
	v_lshl_add_u64 v[152:153], s[4:5], 0, v[152:153]
	v_lshl_add_u64 v[152:153], v[152:153], 0, v[0:1]
	v_pk_mul_f32 v[128:129], v[128:129], v[156:157] op_sel_hi:[1,0]
	v_pk_mul_f32 v[126:127], v[126:127], v[156:157] op_sel_hi:[1,0]
	v_pk_mul_f32 v[154:155], v[124:125], v[156:157] op_sel_hi:[1,0]
	v_pk_mul_f32 v[124:125], v[122:123], v[156:157] op_sel_hi:[1,0]
	v_cvt_pk_bf16_f32 v122, v126, v127
	v_mov_b32_e32 v126, 0
	v_mov_b32_e32 v127, 0
	v_cvt_pk_bf16_f32 v123, v128, v129
	v_mov_b32_e32 v128, 0
	v_mov_b32_e32 v129, 0
	v_pk_mul_f32 v[118:119], v[118:119], v[156:157] op_sel_hi:[1,0]
	v_cvt_pk_bf16_f32 v124, v124, v125
	v_cvt_pk_bf16_f32 v125, v154, v155
	flat_store_dwordx4 v[152:153], v[122:125]
	v_pk_mul_f32 v[120:121], v[120:121], v[156:157] op_sel_hi:[1,0]
	v_pk_mul_f32 v[112:113], v[112:113], v[158:159] op_sel_hi:[1,0]
	v_mov_b32_e32 v124, 0
	v_mov_b32_e32 v125, 0
	v_pk_mul_f32 v[122:123], v[116:117], v[156:157] op_sel_hi:[1,0]
	v_pk_mul_f32 v[116:117], v[114:115], v[156:157] op_sel_hi:[1,0]
	v_cvt_pk_bf16_f32 v114, v118, v119
	v_mov_b32_e32 v118, 0
	v_mov_b32_e32 v119, 0
	v_cvt_pk_bf16_f32 v115, v120, v121
	v_mov_b32_e32 v120, 0
	v_mov_b32_e32 v121, 0
	v_pk_mul_f32 v[110:111], v[110:111], v[158:159] op_sel_hi:[1,0]
	v_cvt_pk_bf16_f32 v116, v116, v117
	v_cvt_pk_bf16_f32 v117, v122, v123
	v_mov_b32_e32 v122, 0
	v_mov_b32_e32 v123, 0
	flat_store_dwordx4 v[152:153], v[114:117] offset:256
	v_pk_mul_f32 v[102:103], v[102:103], v[158:159] op_sel_hi:[1,0]
	v_pk_mul_f32 v[104:105], v[104:105], v[158:159] op_sel_hi:[1,0]
	v_or_b32_e32 v114, 16, v144
	v_ashrrev_i32_e32 v115, 31, v114
	v_lshlrev_b64 v[114:115], 9, v[114:115]
	v_lshl_add_u64 v[114:115], s[4:5], 0, v[114:115]
	v_lshl_add_u64 v[114:115], v[114:115], 0, v[0:1]
	v_pk_mul_f32 v[116:117], v[108:109], v[158:159] op_sel_hi:[1,0]
	v_pk_mul_f32 v[108:109], v[106:107], v[158:159] op_sel_hi:[1,0]
	v_cvt_pk_bf16_f32 v106, v110, v111
	v_mov_b32_e32 v110, 0
	v_mov_b32_e32 v111, 0
	v_cvt_pk_bf16_f32 v107, v112, v113
	v_mov_b32_e32 v112, 0
	v_mov_b32_e32 v113, 0
	v_pk_mul_f32 v[96:97], v[96:97], v[160:161] op_sel_hi:[1,0]
	v_cvt_pk_bf16_f32 v108, v108, v109
	v_cvt_pk_bf16_f32 v109, v116, v117
	v_mov_b32_e32 v116, 0
	v_mov_b32_e32 v117, 0
	flat_store_dwordx4 v[114:115], v[106:109]
	v_pk_mul_f32 v[94:95], v[94:95], v[160:161] op_sel_hi:[1,0]
	v_rsq_f32_e32 v148, v148
	v_mov_b32_e32 v108, 0
	v_mov_b32_e32 v109, 0
	v_pk_mul_f32 v[106:107], v[100:101], v[158:159] op_sel_hi:[1,0]
	v_pk_mul_f32 v[100:101], v[98:99], v[158:159] op_sel_hi:[1,0]
	v_cvt_pk_bf16_f32 v98, v102, v103
	v_mov_b32_e32 v102, 0
	v_mov_b32_e32 v103, 0
	v_cvt_pk_bf16_f32 v99, v104, v105
	v_mov_b32_e32 v104, 0
	v_mov_b32_e32 v105, 0
	v_pk_mul_f32 v[86:87], v[86:87], v[160:161] op_sel_hi:[1,0]
	v_cvt_pk_bf16_f32 v100, v100, v101
	v_cvt_pk_bf16_f32 v101, v106, v107
	v_mov_b32_e32 v106, 0
	v_mov_b32_e32 v107, 0
	flat_store_dwordx4 v[114:115], v[98:101] offset:256
	v_pk_mul_f32 v[88:89], v[88:89], v[160:161] op_sel_hi:[1,0]
	v_cndmask_b32_e64 v162, v148, 1.0, s[40:41]
	v_mov_b32_e32 v114, 0
	v_mov_b32_e32 v115, 0
	v_or_b32_e32 v98, 32, v144
	v_ashrrev_i32_e32 v99, 31, v98
	v_lshlrev_b64 v[98:99], 9, v[98:99]
	v_lshl_add_u64 v[98:99], s[4:5], 0, v[98:99]
	v_lshl_add_u64 v[98:99], v[98:99], 0, v[0:1]
	v_pk_mul_f32 v[100:101], v[92:93], v[160:161] op_sel_hi:[1,0]
	v_pk_mul_f32 v[92:93], v[90:91], v[160:161] op_sel_hi:[1,0]
	v_cvt_pk_bf16_f32 v90, v94, v95
	v_mov_b32_e32 v94, 0
	v_mov_b32_e32 v95, 0
	v_cvt_pk_bf16_f32 v91, v96, v97
	v_mov_b32_e32 v96, 0
	v_mov_b32_e32 v97, 0
	v_pk_mul_f32 v[80:81], v[80:81], v[162:163] op_sel_hi:[1,0]
	v_cvt_pk_bf16_f32 v92, v92, v93
	v_cvt_pk_bf16_f32 v93, v100, v101
	v_mov_b32_e32 v100, 0
	v_mov_b32_e32 v101, 0
	flat_store_dwordx4 v[98:99], v[90:93]
	v_pk_mul_f32 v[78:79], v[78:79], v[162:163] op_sel_hi:[1,0]
	v_pk_mul_f32 v[72:73], v[72:73], v[162:163] op_sel_hi:[1,0]
	v_mov_b32_e32 v92, 0
	v_mov_b32_e32 v93, 0
	v_pk_mul_f32 v[90:91], v[84:85], v[160:161] op_sel_hi:[1,0]
	v_pk_mul_f32 v[84:85], v[82:83], v[160:161] op_sel_hi:[1,0]
	v_cvt_pk_bf16_f32 v82, v86, v87
	v_mov_b32_e32 v86, 0
	v_mov_b32_e32 v87, 0
	v_cvt_pk_bf16_f32 v83, v88, v89
	v_mov_b32_e32 v88, 0
	v_mov_b32_e32 v89, 0
	v_pk_mul_f32 v[70:71], v[70:71], v[162:163] op_sel_hi:[1,0]
	v_cvt_pk_bf16_f32 v84, v84, v85
	v_cvt_pk_bf16_f32 v85, v90, v91
	v_mov_b32_e32 v90, 0
	v_mov_b32_e32 v91, 0
	flat_store_dwordx4 v[98:99], v[82:85] offset:256
	v_pk_mul_f32 v[62:63], v[62:63], v[150:151] op_sel_hi:[1,0]
	v_pk_mul_f32 v[64:65], v[64:65], v[150:151] op_sel_hi:[1,0]
	v_mov_b32_e32 v98, 0
	v_mov_b32_e32 v99, 0
	v_or_b32_e32 v82, 48, v144
	v_ashrrev_i32_e32 v83, 31, v82
	v_lshlrev_b64 v[82:83], 9, v[82:83]
	v_lshl_add_u64 v[82:83], s[4:5], 0, v[82:83]
	v_lshl_add_u64 v[82:83], v[82:83], 0, v[0:1]
	v_pk_mul_f32 v[84:85], v[76:77], v[162:163] op_sel_hi:[1,0]
	v_pk_mul_f32 v[76:77], v[74:75], v[162:163] op_sel_hi:[1,0]
	v_cvt_pk_bf16_f32 v74, v78, v79
	v_mov_b32_e32 v78, 0
	v_mov_b32_e32 v79, 0
	v_cvt_pk_bf16_f32 v75, v80, v81
	v_mov_b32_e32 v80, 0
	v_mov_b32_e32 v81, 0
	v_cndmask_b32_e64 v148, v146, 1.0, s[40:41]
	v_cvt_pk_bf16_f32 v76, v76, v77
	v_cvt_pk_bf16_f32 v77, v84, v85
	v_mov_b32_e32 v84, 0
	v_mov_b32_e32 v85, 0
	flat_store_dwordx4 v[82:83], v[74:77]
	v_pk_mul_f32 v[56:57], v[56:57], v[150:151] op_sel_hi:[1,0]
	v_pk_mul_f32 v[54:55], v[54:55], v[150:151] op_sel_hi:[1,0]
	v_mov_b32_e32 v76, 0
	v_mov_b32_e32 v77, 0
	v_pk_mul_f32 v[74:75], v[68:69], v[162:163] op_sel_hi:[1,0]
	v_pk_mul_f32 v[68:69], v[66:67], v[162:163] op_sel_hi:[1,0]
	v_cvt_pk_bf16_f32 v66, v70, v71
	v_cvt_pk_bf16_f32 v67, v72, v73
	v_mov_b32_e32 v72, 0
	v_mov_b32_e32 v73, 0
	v_pk_mul_f32 v[70:71], v[60:61], v[150:151] op_sel_hi:[1,0]
	v_cvt_pk_bf16_f32 v68, v68, v69
	v_cvt_pk_bf16_f32 v69, v74, v75
	v_mov_b32_e32 v74, 0
	v_mov_b32_e32 v75, 0
	flat_store_dwordx4 v[82:83], v[66:69] offset:256
	v_pk_mul_f32 v[60:61], v[58:59], v[150:151] op_sel_hi:[1,0]
	v_cvt_pk_bf16_f32 v58, v62, v63
	v_mov_b32_e32 v82, 0
	v_mov_b32_e32 v83, 0
	v_cvt_pk_bf16_f32 v59, v64, v65
	v_mov_b32_e32 v64, 0
	v_mov_b32_e32 v65, 0
	v_pk_mul_f32 v[50:51], v[50:51], v[148:149] op_sel_hi:[1,0]
	v_lshlrev_b64 v[66:67], 9, v[144:145]
	v_lshl_add_u64 v[66:67], s[4:5], 0, v[66:67]
	v_lshl_add_u64 v[66:67], v[66:67], 0, v[0:1]
	s_mov_b32 s4, 0x10000
	v_add_co_u32_e32 v62, vcc, s4, v66
	v_cvt_pk_bf16_f32 v60, v60, v61
	v_cvt_pk_bf16_f32 v61, v70, v71
	v_mov_b32_e32 v70, 0
	v_mov_b32_e32 v71, 0
	v_lshl_add_u64 v[68:69], v[66:67], 0, s[84:85]
	s_nop 0
	v_addc_co_u32_e32 v63, vcc, 0, v67, vcc
	flat_store_dwordx4 v[62:63], v[58:61]
	s_mov_b64 s[4:5], 0x12000
	v_cndmask_b32_e64 v146, v151, 1.0, s[40:41]
	v_mov_b32_e32 v60, 0
	v_mov_b32_e32 v61, 0
	v_mov_b32_e32 v62, 0
	v_mov_b32_e32 v63, 0
	v_pk_mul_f32 v[58:59], v[48:49], v[150:151] op_sel_hi:[1,0]
	v_pk_mul_f32 v[48:49], v[46:47], v[150:151] op_sel_hi:[1,0]
	v_cvt_pk_bf16_f32 v46, v54, v55
	v_mov_b32_e32 v54, 0
	v_mov_b32_e32 v55, 0
	v_cvt_pk_bf16_f32 v47, v56, v57
	v_mov_b32_e32 v56, 0
	v_mov_b32_e32 v57, 0
	v_pk_mul_f32 v[40:41], v[40:41], v[148:149] op_sel_hi:[1,0]
	v_cvt_pk_bf16_f32 v48, v48, v49
	v_cvt_pk_bf16_f32 v49, v58, v59
	v_mov_b32_e32 v58, 0
	v_mov_b32_e32 v59, 0
	flat_store_dwordx4 v[68:69], v[46:49] offset:256
	v_pk_mul_f32 v[38:39], v[38:39], v[148:149] op_sel_hi:[1,0]
	v_pk_mul_f32 v[34:35], v[34:35], v[146:147] op_sel_hi:[1,0]
	v_mov_b32_e32 v68, 0
	v_mov_b32_e32 v69, 0
	v_lshl_add_u64 v[46:47], v[66:67], 0, s[4:5]
	v_pk_mul_f32 v[48:49], v[52:53], v[148:149] op_sel_hi:[1,0]
	s_mov_b32 s4, 0x12000
	v_pk_mul_f32 v[52:53], v[44:45], v[148:149] op_sel_hi:[1,0]
	v_pk_mul_f32 v[44:45], v[42:43], v[148:149] op_sel_hi:[1,0]
	v_cvt_pk_bf16_f32 v42, v50, v51
	v_mov_b32_e32 v50, 0
	v_mov_b32_e32 v51, 0
	v_cvt_pk_bf16_f32 v43, v48, v49
	v_add_co_u32_e32 v48, vcc, s4, v66
	v_cvt_pk_bf16_f32 v44, v44, v45
	v_cvt_pk_bf16_f32 v45, v52, v53
	v_mov_b32_e32 v52, 0
	v_mov_b32_e32 v53, 0
	s_mov_b64 s[4:5], 0x14000
	s_nop 0
	v_addc_co_u32_e32 v49, vcc, 0, v67, vcc
	flat_store_dwordx4 v[48:49], v[42:45]
	v_pk_mul_f32 v[24:25], v[24:25], v[146:147] op_sel_hi:[1,0]
	v_pk_mul_f32 v[22:23], v[22:23], v[146:147] op_sel_hi:[1,0]
	v_mov_b32_e32 v44, 0
	v_mov_b32_e32 v45, 0
	v_mov_b32_e32 v48, 0
	v_mov_b32_e32 v49, 0
	v_pk_mul_f32 v[42:43], v[32:33], v[148:149] op_sel_hi:[1,0]
	v_pk_mul_f32 v[32:33], v[30:31], v[148:149] op_sel_hi:[1,0]
	v_cvt_pk_bf16_f32 v30, v38, v39
	v_mov_b32_e32 v38, 0
	v_mov_b32_e32 v39, 0
	v_cvt_pk_bf16_f32 v31, v40, v41
	v_mov_b32_e32 v40, 0
	v_mov_b32_e32 v41, 0
	v_pk_mul_f32 v[18:19], v[18:19], v[142:143] op_sel_hi:[1,0]
	v_cvt_pk_bf16_f32 v32, v32, v33
	v_cvt_pk_bf16_f32 v33, v42, v43
	v_mov_b32_e32 v42, 0
	v_mov_b32_e32 v43, 0
	flat_store_dwordx4 v[46:47], v[30:33] offset:256
	v_pk_mul_f32 v[8:9], v[8:9], v[142:143] op_sel_hi:[1,0]
	v_pk_mul_f32 v[6:7], v[6:7], v[142:143] op_sel_hi:[1,0]
	v_mov_b32_e32 v46, 0
	v_mov_b32_e32 v47, 0
	v_lshl_add_u64 v[30:31], v[66:67], 0, s[4:5]
	v_pk_mul_f32 v[32:33], v[36:37], v[146:147] op_sel_hi:[1,0]
	s_mov_b32 s4, 0x14000
	v_pk_mul_f32 v[36:37], v[28:29], v[146:147] op_sel_hi:[1,0]
	v_pk_mul_f32 v[28:29], v[26:27], v[146:147] op_sel_hi:[1,0]
	v_cvt_pk_bf16_f32 v26, v34, v35
	v_mov_b32_e32 v34, 0
	v_mov_b32_e32 v35, 0
	v_cvt_pk_bf16_f32 v27, v32, v33
	v_add_co_u32_e32 v32, vcc, s4, v66
	v_cvt_pk_bf16_f32 v28, v28, v29
	v_cvt_pk_bf16_f32 v29, v36, v37
	v_mov_b32_e32 v36, 0
	v_mov_b32_e32 v37, 0
	s_mov_b64 s[4:5], 0x16000
	s_nop 0
	v_addc_co_u32_e32 v33, vcc, 0, v67, vcc
	flat_store_dwordx4 v[32:33], v[26:29]
	s_nop 1
	v_pk_mul_f32 v[26:27], v[16:17], v[146:147] op_sel_hi:[1,0]
	v_mov_b32_e32 v28, 0
	v_mov_b32_e32 v29, 0
	v_mov_b32_e32 v32, 0
	v_mov_b32_e32 v33, 0
	v_pk_mul_f32 v[16:17], v[14:15], v[146:147] op_sel_hi:[1,0]
	v_cvt_pk_bf16_f32 v14, v22, v23
	v_mov_b32_e32 v22, 0
	v_mov_b32_e32 v23, 0
	v_cvt_pk_bf16_f32 v15, v24, v25
	v_mov_b32_e32 v24, 0
	v_mov_b32_e32 v25, 0
	s_nop 0
	v_cvt_pk_bf16_f32 v16, v16, v17
	v_cvt_pk_bf16_f32 v17, v26, v27
	v_mov_b32_e32 v26, 0
	v_mov_b32_e32 v27, 0
	flat_store_dwordx4 v[30:31], v[14:17] offset:256
	s_nop 1
	v_lshl_add_u64 v[14:15], v[66:67], 0, s[4:5]
	v_mov_b32_e32 v30, 0
	v_mov_b32_e32 v31, 0
	v_pk_mul_f32 v[16:17], v[20:21], v[142:143] op_sel_hi:[1,0]
	s_mov_b32 s4, 0x16000
	v_pk_mul_f32 v[20:21], v[12:13], v[142:143] op_sel_hi:[1,0]
	v_pk_mul_f32 v[12:13], v[10:11], v[142:143] op_sel_hi:[1,0]
	v_cvt_pk_bf16_f32 v10, v18, v19
	v_mov_b32_e32 v18, 0
	v_mov_b32_e32 v19, 0
	v_cvt_pk_bf16_f32 v11, v16, v17
	v_add_co_u32_e32 v16, vcc, s4, v66
	v_mov_b32_e32 v66, 0
	v_cvt_pk_bf16_f32 v12, v12, v13
	v_cvt_pk_bf16_f32 v13, v20, v21
	v_mov_b32_e32 v20, 0
	v_mov_b32_e32 v21, 0
	s_mov_b64 s[4:5], -1
	s_nop 0
	v_addc_co_u32_e32 v17, vcc, 0, v67, vcc
	v_mov_b32_e32 v67, 0
	flat_store_dwordx4 v[16:17], v[10:13]
	s_andn2_b64 vcc, exec, s[38:39]
	s_nop 0
	v_mov_b32_e32 v12, 0
	v_mov_b32_e32 v13, 0
	v_mov_b32_e32 v16, 0
	v_mov_b32_e32 v17, 0
	v_pk_mul_f32 v[10:11], v[4:5], v[142:143] op_sel_hi:[1,0]
	v_pk_mul_f32 v[4:5], v[2:3], v[142:143] op_sel_hi:[1,0]
	v_cvt_pk_bf16_f32 v2, v6, v7
	v_mov_b32_e32 v6, 0
	v_mov_b32_e32 v7, 0
	v_cvt_pk_bf16_f32 v3, v8, v9
	v_mov_b32_e32 v8, 0
	v_mov_b32_e32 v9, 0
	s_nop 0
	v_cvt_pk_bf16_f32 v4, v4, v5
	v_cvt_pk_bf16_f32 v5, v10, v11
	v_mov_b32_e32 v10, 0
	v_mov_b32_e32 v11, 0
	flat_store_dwordx4 v[14:15], v[2:5] offset:256
	s_cbranch_vccnz .LBB0_179
	s_andn2_b64 vcc, exec, s[6:7]
	s_cbranch_vccnz .LBB0_178
	s_barrier
	s_branch .LBB0_178
